# grid barrier: all workgroups poll the monotonic cross-XCD arrival counter against (gen+1)*nxcd; release-generation adds removed from the leader path
# speedup vs baseline: 1.0176x; 1.0013x over previous
;   DI unsigned* bar() const { return (unsigned*)(ws + OFF_BAR); }
; __device__ __forceinline__ unsigned xb_ld(unsigned* p)              { return __hip_atomic_load(p, __ATOMIC_RELAXED, __HIP_MEMORY_SCOPE_AGENT); }
; __device__ __forceinline__ unsigned xb_add(unsigned* p, unsigned v) { return __hip_atomic_fetch_add(p, v, __ATOMIC_RELAXED, __HIP_MEMORY_SCOPE_AGENT); }
; #define XB_SPIN(cond, bar) do { unsigned _sp = 0; while (cond) { __builtin_amdgcn_s_sleep(1); \
;     if ((++_sp & 255u) == 0u) { if (xb_ld(&(bar)[XB_TMO])) break; if (_sp > XB_SPIN_CAP) { atomicAdd(&(bar)[XB_TMO], 1u); break; } } } } while (0)
; __device__ __forceinline__ void xcd_barrier(const XcdBarrier& b) {
;     ...
;     if (threadIdx.x == 0) {
;         unsigned* bar = b.bar;
;         __builtin_amdgcn_s_waitcnt(0);
;         unsigned nloc = b.st[0], nx = b.st[1];
;         if (nloc == 0u) { xcd_barrier_complete(bar, b.x, nloc, nx); b.st[0] = nloc; b.st[1] = nx; }
;         const unsigned old = xb_add(&bar[XB_XSUB(b.x)], 1u);
;         const unsigned gen = old / nloc;
;         if (old + 1u == (gen + 1u) * nloc) {
;             __builtin_amdgcn_fence(__ATOMIC_RELEASE, "agent");
;             asm volatile("s_waitcnt vmcnt(0)" ::: "memory");
;             const unsigned og = xb_add(&bar[XB_TOP], 1u);
;             const unsigned tg = og / nx;
;             if (og + 1u == (tg + 1u) * nx) xb_add(&bar[XB_TOPGEN], 1u);
;             else XB_SPIN(xb_ld(&bar[XB_TOPGEN]) == tg, bar);
;             __builtin_amdgcn_fence(__ATOMIC_ACQUIRE, "agent");
;             xb_add(&bar[XB_XGEN(b.x)], 1u);
;             asm volatile("s_waitcnt vmcnt(0)" ::: "memory");
;         } else {
;             XB_SPIN(xb_ld(&bar[XB_XGEN(b.x)]) == gen, bar);
;             __builtin_amdgcn_fence(__ATOMIC_ACQUIRE, "agent");
;             asm volatile("s_waitcnt vmcnt(0)" ::: "memory");
;         }
.Lgs_151:
	s_or_b64 exec, exec, s[6:7]
	v_cvt_f32_u32_e32 v4, v2
	s_waitcnt vmcnt(0)
	v_readfirstlane_b32 s4, v3
	v_sub_u32_e32 v3, 0, v2
	v_rcp_iflag_f32_e32 v4, v4
	v_add_u32_e32 v5, s4, v0
	v_mul_f32_e32 v4, 0x4f7ffffe, v4
	v_cvt_u32_f32_e32 v4, v4
	v_mul_lo_u32 v0, v3, v4
	v_mul_hi_u32 v0, v4, v0
	v_add_u32_e32 v0, v4, v0
	v_mul_hi_u32 v0, v5, v0
	v_mul_lo_u32 v3, v0, v2
	v_sub_u32_e32 v3, v5, v3
	v_add_u32_e32 v4, 1, v0
	v_cmp_ge_u32_e32 vcc, v3, v2
	s_nop 1
	v_cndmask_b32_e32 v0, v0, v4, vcc
	v_sub_u32_e32 v4, v3, v2
	v_cndmask_b32_e32 v3, v3, v4, vcc
	v_add_u32_e32 v4, 1, v0
	v_cmp_ge_u32_e32 vcc, v3, v2
	v_add_u32_e32 v3, 1, v5
	s_nop 0
	v_cndmask_b32_e32 v0, v0, v4, vcc
	v_mul_lo_u32 v4, v2, v0
	v_add_u32_e32 v2, v4, v2
	v_cmp_ne_u32_e32 vcc, v3, v2
	s_and_saveexec_b64 s[4:5], vcc
	s_xor_b64 s[4:5], exec, s[4:5]
	s_cbranch_execz .Lgs_165
	s_waitcnt lgkmcnt(0)
	v_mad_u32_u24 v6, v0, v1, v1
	s_add_u32 s10, s22, 0x1e6c4400
	s_addc_u32 s11, s23, 0
	v_mov_b32_e32 v1, 0
	global_load_dword v1, v1, s[10:11] sc1
	s_waitcnt vmcnt(0)
	v_cmp_lt_u32_e32 vcc, v1, v6
	s_and_saveexec_b64 s[6:7], vcc
	s_cbranch_execz .Lgs_164
	s_add_u32 s8, s22, 0x1e6c1200
	s_addc_u32 s9, s23, 0
	s_mov_b32 s26, 1
	s_mov_b64 s[12:13], 0
	v_mov_b32_e32 v1, 0
	s_branch .Lgs_155

;   DI unsigned* bar() const { return (unsigned*)(ws + OFF_BAR); }
; __device__ __forceinline__ unsigned xb_ld(unsigned* p)              { return __hip_atomic_load(p, __ATOMIC_RELAXED, __HIP_MEMORY_SCOPE_AGENT); }
; __device__ __forceinline__ unsigned xb_add(unsigned* p, unsigned v) { return __hip_atomic_fetch_add(p, v, __ATOMIC_RELAXED, __HIP_MEMORY_SCOPE_AGENT); }
; #define XB_SPIN(cond, bar) do { unsigned _sp = 0; while (cond) { __builtin_amdgcn_s_sleep(1); \
;     if ((++_sp & 255u) == 0u) { if (xb_ld(&(bar)[XB_TMO])) break; if (_sp > XB_SPIN_CAP) { atomicAdd(&(bar)[XB_TMO], 1u); break; } } } } while (0)
; __device__ __forceinline__ void xcd_barrier(const XcdBarrier& b) {
;     ...
;             else XB_SPIN(xb_ld(&bar[XB_TOPGEN]) == tg, bar);
;             __builtin_amdgcn_fence(__ATOMIC_ACQUIRE, "agent");
;             xb_add(&bar[XB_XGEN(b.x)], 1u);
;             asm volatile("s_waitcnt vmcnt(0)" ::: "memory");
;         } else {
;             XB_SPIN(xb_ld(&bar[XB_XGEN(b.x)]) == gen, bar);
.Lgs_159:
	global_load_dword v2, v1, s[10:11] sc1
	s_add_i32 s26, s26, 1
	s_mov_b64 s[18:19], -1
	s_waitcnt vmcnt(0)
	v_cmp_ge_u32_e32 vcc, v2, v6
	s_orn2_b64 s[16:17], vcc, exec
	s_branch .Lgs_154

;   DI unsigned* bar() const { return (unsigned*)(ws + OFF_BAR); }
; __device__ __forceinline__ unsigned xb_ld(unsigned* p)              { return __hip_atomic_load(p, __ATOMIC_RELAXED, __HIP_MEMORY_SCOPE_AGENT); }
; __device__ __forceinline__ unsigned xb_add(unsigned* p, unsigned v) { return __hip_atomic_fetch_add(p, v, __ATOMIC_RELAXED, __HIP_MEMORY_SCOPE_AGENT); }
; #define XB_SPIN(cond, bar) do { unsigned _sp = 0; while (cond) { __builtin_amdgcn_s_sleep(1); \
;     if ((++_sp & 255u) == 0u) { if (xb_ld(&(bar)[XB_TMO])) break; if (_sp > XB_SPIN_CAP) { atomicAdd(&(bar)[XB_TMO], 1u); break; } } } } while (0)
; __device__ __forceinline__ void xcd_barrier(const XcdBarrier& b) {
;     ...
;             const unsigned og = xb_add(&bar[XB_TOP], 1u);
;             const unsigned tg = og / nx;
;             if (og + 1u == (tg + 1u) * nx) xb_add(&bar[XB_TOPGEN], 1u);
;             else XB_SPIN(xb_ld(&bar[XB_TOPGEN]) == tg, bar);
;             __builtin_amdgcn_fence(__ATOMIC_ACQUIRE, "agent");
;             xb_add(&bar[XB_XGEN(b.x)], 1u);
.Lgs_168:
	s_or_b64 exec, exec, s[6:7]
	v_cvt_f32_u32_e32 v3, v1
	s_waitcnt vmcnt(0)
	v_readfirstlane_b32 s4, v2
	s_add_u32 s6, s22, 0x1e6c4500
	s_addc_u32 s7, s23, 0
	s_add_u32 s98, s22, 0x1e6c4400
	s_addc_u32 s99, s23, 0
	v_rcp_iflag_f32_e32 v3, v3
	v_add_u32_e32 v0, s4, v0
	v_add_u32_e32 v4, 1, v0
	s_mov_b64 s[8:9], 0
	v_mul_f32_e32 v2, 0x4f7ffffe, v3
	v_cvt_u32_f32_e32 v2, v2
	v_sub_u32_e32 v3, 0, v1
	v_mul_lo_u32 v3, v3, v2
	v_mul_hi_u32 v3, v2, v3
	v_add_u32_e32 v2, v2, v3
	v_mul_hi_u32 v2, v0, v2
	v_mul_lo_u32 v3, v2, v1
	v_sub_u32_e32 v0, v0, v3
	v_add_u32_e32 v5, 1, v2
	v_cmp_ge_u32_e32 vcc, v0, v1
	v_sub_u32_e32 v3, v0, v1
	s_nop 0
	v_cndmask_b32_e32 v2, v2, v5, vcc
	v_cndmask_b32_e32 v0, v0, v3, vcc
	v_add_u32_e32 v3, 1, v2
	v_cmp_ge_u32_e32 vcc, v0, v1
	s_nop 1
	v_cndmask_b32_e32 v2, v2, v3, vcc
	v_mul_lo_u32 v0, v1, v2
	v_add_u32_e32 v0, v0, v1
	v_cmp_ne_u32_e32 vcc, v4, v0
	v_mov_b32_e32 v6, v0
	v_mov_b64_e32 v[0:1], s[6:7]
	s_and_saveexec_b64 s[4:5], vcc
	s_cbranch_execz .Lgs_180
	v_mov_b32_e32 v0, 0
	global_load_dword v1, v0, s[98:99] sc1
	s_mov_b64 s[12:13], 0
	s_waitcnt vmcnt(0)
	v_cmp_lt_u32_e32 vcc, v1, v6
	s_and_saveexec_b64 s[10:11], vcc
	s_cbranch_execz .Lgs_179
	s_add_u32 s8, s22, 0x1e6c1200
	s_addc_u32 s9, s23, 0
	s_mov_b32 s26, 1
	s_branch .Lgs_172

;   DI unsigned* bar() const { return (unsigned*)(ws + OFF_BAR); }
; __device__ __forceinline__ unsigned xb_ld(unsigned* p)              { return __hip_atomic_load(p, __ATOMIC_RELAXED, __HIP_MEMORY_SCOPE_AGENT); }
; __device__ __forceinline__ unsigned xb_add(unsigned* p, unsigned v) { return __hip_atomic_fetch_add(p, v, __ATOMIC_RELAXED, __HIP_MEMORY_SCOPE_AGENT); }
; #define XB_SPIN(cond, bar) do { unsigned _sp = 0; while (cond) { __builtin_amdgcn_s_sleep(1); \
;     if ((++_sp & 255u) == 0u) { if (xb_ld(&(bar)[XB_TMO])) break; if (_sp > XB_SPIN_CAP) { atomicAdd(&(bar)[XB_TMO], 1u); break; } } } } while (0)
; __device__ __forceinline__ void xcd_barrier(const XcdBarrier& b) {
;     ...
;             const unsigned og = xb_add(&bar[XB_TOP], 1u);
;             const unsigned tg = og / nx;
;             if (og + 1u == (tg + 1u) * nx) xb_add(&bar[XB_TOPGEN], 1u);
;             else XB_SPIN(xb_ld(&bar[XB_TOPGEN]) == tg, bar);
;             __builtin_amdgcn_fence(__ATOMIC_ACQUIRE, "agent");
;             xb_add(&bar[XB_XGEN(b.x)], 1u);
.Lgs_176:
	global_load_dword v1, v0, s[98:99] sc1
	s_add_i32 s26, s26, 1
	s_mov_b64 s[16:17], -1
	s_waitcnt vmcnt(0)
	v_cmp_ge_u32_e32 vcc, v1, v6
	s_orn2_b64 s[24:25], vcc, exec
	s_branch .Lgs_171

;   DI unsigned* bar() const { return (unsigned*)(ws + OFF_BAR); }
; __device__ __forceinline__ unsigned xb_add(unsigned* p, unsigned v) { return __hip_atomic_fetch_add(p, v, __ATOMIC_RELAXED, __HIP_MEMORY_SCOPE_AGENT); }
; __device__ __forceinline__ void xcd_barrier(const XcdBarrier& b) {
;     ...
;             __builtin_amdgcn_fence(__ATOMIC_ACQUIRE, "agent");
;             xb_add(&bar[XB_XGEN(b.x)], 1u);
;             asm volatile("s_waitcnt vmcnt(0)" ::: "memory");
.Lgs_182:
	s_or_b64 exec, exec, s[4:5]
	s_mov_b64 s[4:5], exec
	v_mbcnt_lo_u32_b32 v0, s4, 0
	v_mbcnt_hi_u32_b32 v0, s5, v0
	v_cmp_eq_u32_e32 vcc, 0, v0
	s_waitcnt vmcnt(0)
	buffer_inv sc1
	s_and_saveexec_b64 s[6:7], vcc
	s_cbranch_execz .Lgs_184
	s_bcnt1_i32_b64 s4, s[4:5]
	v_mov_b32_e32 v0, 0x2000
	v_mov_b32_e32 v1, s4
.Lgs_184:
	s_or_b64 exec, exec, s[6:7]
	s_waitcnt vmcnt(0)

;   DI unsigned* bar() const { return (unsigned*)(ws + OFF_BAR); }
; __device__ __forceinline__ unsigned xb_add(unsigned* p, unsigned v) { return __hip_atomic_fetch_add(p, v, __ATOMIC_RELAXED, __HIP_MEMORY_SCOPE_AGENT); }
; __device__ __forceinline__ void xcd_barrier(const XcdBarrier& b) {
;     ...
;             __builtin_amdgcn_fence(__ATOMIC_ACQUIRE, "agent");
;             xb_add(&bar[XB_XGEN(b.x)], 1u);
;             asm volatile("s_waitcnt vmcnt(0)" ::: "memory");
.LBB0_182:
	s_or_b64 exec, exec, s[4:5]
	s_mov_b64 s[4:5], exec
	v_mbcnt_lo_u32_b32 v0, s4, 0
	v_mbcnt_hi_u32_b32 v0, s5, v0
	v_cmp_eq_u32_e32 vcc, 0, v0
	s_waitcnt vmcnt(0)
	buffer_inv sc1
	s_and_saveexec_b64 s[6:7], vcc
	s_cbranch_execz .LBB0_184
	s_bcnt1_i32_b64 s4, s[4:5]
	v_mov_b32_e32 v0, 0x2000
	v_mov_b32_e32 v1, s4
.LBB0_184:
	s_or_b64 exec, exec, s[6:7]
	s_waitcnt vmcnt(0)

;   DI unsigned* bar() const { return (unsigned*)(ws + OFF_BAR); }
; __device__ __forceinline__ unsigned xb_add(unsigned* p, unsigned v) { return __hip_atomic_fetch_add(p, v, __ATOMIC_RELAXED, __HIP_MEMORY_SCOPE_AGENT); }
; __device__ __forceinline__ void xcd_barrier(const XcdBarrier& b) {
;     ...
;             __builtin_amdgcn_fence(__ATOMIC_ACQUIRE, "agent");
;             xb_add(&bar[XB_XGEN(b.x)], 1u);
;             asm volatile("s_waitcnt vmcnt(0)" ::: "memory");
.LBB0_281:
	s_or_b64 exec, exec, s[4:5]
	s_mov_b64 s[4:5], exec
	v_mbcnt_lo_u32_b32 v0, s4, 0
	v_mbcnt_hi_u32_b32 v0, s5, v0
	v_cmp_eq_u32_e32 vcc, 0, v0
	s_waitcnt vmcnt(0)
	buffer_inv sc1
	s_and_saveexec_b64 s[6:7], vcc
	s_cbranch_execz .LBB0_283
	s_bcnt1_i32_b64 s4, s[4:5]
	v_mov_b32_e32 v0, 0x2000
	v_mov_b32_e32 v1, s4
.LBB0_283:
	s_or_b64 exec, exec, s[6:7]
	s_waitcnt vmcnt(0)

;   DI unsigned* bar() const { return (unsigned*)(ws + OFF_BAR); }
; __device__ __forceinline__ unsigned xb_ld(unsigned* p)              { return __hip_atomic_load(p, __ATOMIC_RELAXED, __HIP_MEMORY_SCOPE_AGENT); }
; __device__ __forceinline__ unsigned xb_add(unsigned* p, unsigned v) { return __hip_atomic_fetch_add(p, v, __ATOMIC_RELAXED, __HIP_MEMORY_SCOPE_AGENT); }
; #define XB_SPIN(cond, bar) do { unsigned _sp = 0; while (cond) { __builtin_amdgcn_s_sleep(1); \
;     if ((++_sp & 255u) == 0u) { if (xb_ld(&(bar)[XB_TMO])) break; if (_sp > XB_SPIN_CAP) { atomicAdd(&(bar)[XB_TMO], 1u); break; } } } } while (0)
; __device__ __forceinline__ void xcd_barrier(const XcdBarrier& b) {
;     ...
;     if (threadIdx.x == 0) {
;         unsigned* bar = b.bar;
;         __builtin_amdgcn_s_waitcnt(0);
;         unsigned nloc = b.st[0], nx = b.st[1];
;         if (nloc == 0u) { xcd_barrier_complete(bar, b.x, nloc, nx); b.st[0] = nloc; b.st[1] = nx; }
;         const unsigned old = xb_add(&bar[XB_XSUB(b.x)], 1u);
;         const unsigned gen = old / nloc;
;         if (old + 1u == (gen + 1u) * nloc) {
;             __builtin_amdgcn_fence(__ATOMIC_RELEASE, "agent");
;             asm volatile("s_waitcnt vmcnt(0)" ::: "memory");
;             const unsigned og = xb_add(&bar[XB_TOP], 1u);
;             const unsigned tg = og / nx;
;             if (og + 1u == (tg + 1u) * nx) xb_add(&bar[XB_TOPGEN], 1u);
;             else XB_SPIN(xb_ld(&bar[XB_TOPGEN]) == tg, bar);
;             __builtin_amdgcn_fence(__ATOMIC_ACQUIRE, "agent");
;             xb_add(&bar[XB_XGEN(b.x)], 1u);
;             asm volatile("s_waitcnt vmcnt(0)" ::: "memory");
;         } else {
;             XB_SPIN(xb_ld(&bar[XB_XGEN(b.x)]) == gen, bar);
;             __builtin_amdgcn_fence(__ATOMIC_ACQUIRE, "agent");
;             asm volatile("s_waitcnt vmcnt(0)" ::: "memory");
;         }
.LBB0_643:
	s_or_b64 exec, exec, s[8:9]
	v_cvt_f32_u32_e32 v4, v2
	s_waitcnt vmcnt(0)
	v_readfirstlane_b32 s4, v3
	v_sub_u32_e32 v3, 0, v2
	v_rcp_iflag_f32_e32 v4, v4
	v_add_u32_e32 v5, s4, v0
	v_mul_f32_e32 v4, 0x4f7ffffe, v4
	v_cvt_u32_f32_e32 v4, v4
	v_mul_lo_u32 v0, v3, v4
	v_mul_hi_u32 v0, v4, v0
	v_add_u32_e32 v0, v4, v0
	v_mul_hi_u32 v0, v5, v0
	v_mul_lo_u32 v3, v0, v2
	v_sub_u32_e32 v3, v5, v3
	v_add_u32_e32 v4, 1, v0
	v_cmp_ge_u32_e32 vcc, v3, v2
	s_nop 1
	v_cndmask_b32_e32 v0, v0, v4, vcc
	v_sub_u32_e32 v4, v3, v2
	v_cndmask_b32_e32 v3, v3, v4, vcc
	v_add_u32_e32 v4, 1, v0
	v_cmp_ge_u32_e32 vcc, v3, v2
	v_add_u32_e32 v3, 1, v5
	s_nop 0
	v_cndmask_b32_e32 v0, v0, v4, vcc
	v_mul_lo_u32 v4, v2, v0
	v_add_u32_e32 v2, v4, v2
	v_cmp_ne_u32_e32 vcc, v3, v2
	s_and_saveexec_b64 s[4:5], vcc
	s_xor_b64 s[4:5], exec, s[4:5]
	s_cbranch_execz .LBB0_657
	s_waitcnt lgkmcnt(0)
	v_mad_u32_u24 v6, v0, v1, v1
	s_add_u32 s12, s22, 0x1e6c4400
	s_addc_u32 s13, s23, 0
	v_mov_b32_e32 v1, 0
	global_load_dword v1, v1, s[12:13] sc1
	s_waitcnt vmcnt(0)
	v_cmp_lt_u32_e32 vcc, v1, v6
	s_and_saveexec_b64 s[8:9], vcc
	s_cbranch_execz .LBB0_656
	s_add_u32 s10, s22, 0x1e6c1200
	s_addc_u32 s11, s23, 0
	s_mov_b32 s28, 1
	s_mov_b64 s[14:15], 0
	v_mov_b32_e32 v1, 0
	s_branch .LBB0_647

;   DI unsigned* bar() const { return (unsigned*)(ws + OFF_BAR); }
; __device__ __forceinline__ unsigned xb_ld(unsigned* p)              { return __hip_atomic_load(p, __ATOMIC_RELAXED, __HIP_MEMORY_SCOPE_AGENT); }
; __device__ __forceinline__ unsigned xb_add(unsigned* p, unsigned v) { return __hip_atomic_fetch_add(p, v, __ATOMIC_RELAXED, __HIP_MEMORY_SCOPE_AGENT); }
; #define XB_SPIN(cond, bar) do { unsigned _sp = 0; while (cond) { __builtin_amdgcn_s_sleep(1); \
;     if ((++_sp & 255u) == 0u) { if (xb_ld(&(bar)[XB_TMO])) break; if (_sp > XB_SPIN_CAP) { atomicAdd(&(bar)[XB_TMO], 1u); break; } } } } while (0)
; __device__ __forceinline__ void xcd_barrier(const XcdBarrier& b) {
;     ...
;             else XB_SPIN(xb_ld(&bar[XB_TOPGEN]) == tg, bar);
;             __builtin_amdgcn_fence(__ATOMIC_ACQUIRE, "agent");
;             xb_add(&bar[XB_XGEN(b.x)], 1u);
;             asm volatile("s_waitcnt vmcnt(0)" ::: "memory");
;         } else {
;             XB_SPIN(xb_ld(&bar[XB_XGEN(b.x)]) == gen, bar);
.LBB0_651:
	global_load_dword v2, v1, s[12:13] sc1
	s_add_i32 s28, s28, 1
	s_mov_b64 s[24:25], -1
	s_waitcnt vmcnt(0)
	v_cmp_ge_u32_e32 vcc, v2, v6
	s_orn2_b64 s[18:19], vcc, exec
	s_branch .LBB0_646

;   DI unsigned* bar() const { return (unsigned*)(ws + OFF_BAR); }
; __device__ __forceinline__ unsigned xb_ld(unsigned* p)              { return __hip_atomic_load(p, __ATOMIC_RELAXED, __HIP_MEMORY_SCOPE_AGENT); }
; __device__ __forceinline__ unsigned xb_add(unsigned* p, unsigned v) { return __hip_atomic_fetch_add(p, v, __ATOMIC_RELAXED, __HIP_MEMORY_SCOPE_AGENT); }
; #define XB_SPIN(cond, bar) do { unsigned _sp = 0; while (cond) { __builtin_amdgcn_s_sleep(1); \
;     if ((++_sp & 255u) == 0u) { if (xb_ld(&(bar)[XB_TMO])) break; if (_sp > XB_SPIN_CAP) { atomicAdd(&(bar)[XB_TMO], 1u); break; } } } } while (0)
; __device__ __forceinline__ void xcd_barrier(const XcdBarrier& b) {
;     ...
;             const unsigned og = xb_add(&bar[XB_TOP], 1u);
;             const unsigned tg = og / nx;
;             if (og + 1u == (tg + 1u) * nx) xb_add(&bar[XB_TOPGEN], 1u);
;             else XB_SPIN(xb_ld(&bar[XB_TOPGEN]) == tg, bar);
;             __builtin_amdgcn_fence(__ATOMIC_ACQUIRE, "agent");
;             xb_add(&bar[XB_XGEN(b.x)], 1u);
.LBB0_660:
	s_or_b64 exec, exec, s[8:9]
	v_cvt_f32_u32_e32 v3, v1
	s_waitcnt vmcnt(0)
	v_readfirstlane_b32 s4, v2
	s_add_u32 s8, s22, 0x1e6c4500
	s_addc_u32 s9, s23, 0
	s_add_u32 s98, s22, 0x1e6c4400
	s_addc_u32 s99, s23, 0
	v_rcp_iflag_f32_e32 v3, v3
	v_add_u32_e32 v0, s4, v0
	v_add_u32_e32 v4, 1, v0
	s_mov_b64 s[10:11], 0
	v_mul_f32_e32 v2, 0x4f7ffffe, v3
	v_cvt_u32_f32_e32 v2, v2
	v_sub_u32_e32 v3, 0, v1
	v_mul_lo_u32 v3, v3, v2
	v_mul_hi_u32 v3, v2, v3
	v_add_u32_e32 v2, v2, v3
	v_mul_hi_u32 v2, v0, v2
	v_mul_lo_u32 v3, v2, v1
	v_sub_u32_e32 v0, v0, v3
	v_add_u32_e32 v5, 1, v2
	v_cmp_ge_u32_e32 vcc, v0, v1
	v_sub_u32_e32 v3, v0, v1
	s_nop 0
	v_cndmask_b32_e32 v2, v2, v5, vcc
	v_cndmask_b32_e32 v0, v0, v3, vcc
	v_add_u32_e32 v3, 1, v2
	v_cmp_ge_u32_e32 vcc, v0, v1
	s_nop 1
	v_cndmask_b32_e32 v2, v2, v3, vcc
	v_mul_lo_u32 v0, v1, v2
	v_add_u32_e32 v0, v0, v1
	v_cmp_ne_u32_e32 vcc, v4, v0
	v_mov_b32_e32 v6, v0
	v_mov_b64_e32 v[0:1], s[8:9]
	s_and_saveexec_b64 s[4:5], vcc
	s_cbranch_execz .LBB0_672
	v_mov_b32_e32 v0, 0
	global_load_dword v1, v0, s[98:99] sc1
	s_mov_b64 s[14:15], 0
	s_waitcnt vmcnt(0)
	v_cmp_lt_u32_e32 vcc, v1, v6
	s_and_saveexec_b64 s[12:13], vcc
	s_cbranch_execz .LBB0_671
	s_add_u32 s10, s22, 0x1e6c1200
	s_addc_u32 s11, s23, 0
	s_mov_b32 s28, 1
	s_branch .LBB0_664

;   DI unsigned* bar() const { return (unsigned*)(ws + OFF_BAR); }
; __device__ __forceinline__ unsigned xb_ld(unsigned* p)              { return __hip_atomic_load(p, __ATOMIC_RELAXED, __HIP_MEMORY_SCOPE_AGENT); }
; __device__ __forceinline__ unsigned xb_add(unsigned* p, unsigned v) { return __hip_atomic_fetch_add(p, v, __ATOMIC_RELAXED, __HIP_MEMORY_SCOPE_AGENT); }
; #define XB_SPIN(cond, bar) do { unsigned _sp = 0; while (cond) { __builtin_amdgcn_s_sleep(1); \
;     if ((++_sp & 255u) == 0u) { if (xb_ld(&(bar)[XB_TMO])) break; if (_sp > XB_SPIN_CAP) { atomicAdd(&(bar)[XB_TMO], 1u); break; } } } } while (0)
; __device__ __forceinline__ void xcd_barrier(const XcdBarrier& b) {
;     ...
;             const unsigned og = xb_add(&bar[XB_TOP], 1u);
;             const unsigned tg = og / nx;
;             if (og + 1u == (tg + 1u) * nx) xb_add(&bar[XB_TOPGEN], 1u);
;             else XB_SPIN(xb_ld(&bar[XB_TOPGEN]) == tg, bar);
;             __builtin_amdgcn_fence(__ATOMIC_ACQUIRE, "agent");
;             xb_add(&bar[XB_XGEN(b.x)], 1u);
.LBB0_668:
	global_load_dword v1, v0, s[98:99] sc1
	s_add_i32 s28, s28, 1
	s_mov_b64 s[18:19], -1
	s_waitcnt vmcnt(0)
	v_cmp_ge_u32_e32 vcc, v1, v6
	s_orn2_b64 s[26:27], vcc, exec
	s_branch .LBB0_663

;   DI unsigned* bar() const { return (unsigned*)(ws + OFF_BAR); }
; __device__ __forceinline__ unsigned xb_add(unsigned* p, unsigned v) { return __hip_atomic_fetch_add(p, v, __ATOMIC_RELAXED, __HIP_MEMORY_SCOPE_AGENT); }
; __device__ __forceinline__ void xcd_barrier(const XcdBarrier& b) {
;     ...
;             __builtin_amdgcn_fence(__ATOMIC_ACQUIRE, "agent");
;             xb_add(&bar[XB_XGEN(b.x)], 1u);
;             asm volatile("s_waitcnt vmcnt(0)" ::: "memory");
.LBB0_674:
	s_or_b64 exec, exec, s[4:5]
	s_mov_b64 s[4:5], exec
	v_mbcnt_lo_u32_b32 v0, s4, 0
	v_mbcnt_hi_u32_b32 v0, s5, v0
	v_cmp_eq_u32_e32 vcc, 0, v0
	s_waitcnt vmcnt(0)
	buffer_inv sc1
	s_and_saveexec_b64 s[8:9], vcc
	s_cbranch_execz .LBB0_676
	s_bcnt1_i32_b64 s4, s[4:5]
	v_mov_b32_e32 v0, 0x2000
	v_mov_b32_e32 v1, s4
.LBB0_676:
	s_or_b64 exec, exec, s[8:9]
	s_waitcnt vmcnt(0)

;   DI unsigned* bar() const { return (unsigned*)(ws + OFF_BAR); }
; __device__ __forceinline__ unsigned xb_add(unsigned* p, unsigned v) { return __hip_atomic_fetch_add(p, v, __ATOMIC_RELAXED, __HIP_MEMORY_SCOPE_AGENT); }
; __device__ __forceinline__ void xcd_barrier(const XcdBarrier& b) {
;     ...
;             __builtin_amdgcn_fence(__ATOMIC_ACQUIRE, "agent");
;             xb_add(&bar[XB_XGEN(b.x)], 1u);
;             asm volatile("s_waitcnt vmcnt(0)" ::: "memory");
.LBB0_739:
	s_or_b64 exec, exec, s[4:5]
	s_mov_b64 s[4:5], exec
	v_mbcnt_lo_u32_b32 v0, s4, 0
	v_mbcnt_hi_u32_b32 v0, s5, v0
	v_cmp_eq_u32_e32 vcc, 0, v0
	s_waitcnt vmcnt(0)
	buffer_inv sc1
	s_and_saveexec_b64 s[8:9], vcc
	s_cbranch_execz .LBB0_741
	s_bcnt1_i32_b64 s4, s[4:5]
	v_mov_b32_e32 v0, 0x2000
	v_mov_b32_e32 v1, s4
.LBB0_741:
	s_or_b64 exec, exec, s[8:9]
	s_waitcnt vmcnt(0)

;   DI unsigned* bar() const { return (unsigned*)(ws + OFF_BAR); }
; __device__ __forceinline__ unsigned xb_ld(unsigned* p)              { return __hip_atomic_load(p, __ATOMIC_RELAXED, __HIP_MEMORY_SCOPE_AGENT); }
; __device__ __forceinline__ unsigned xb_add(unsigned* p, unsigned v) { return __hip_atomic_fetch_add(p, v, __ATOMIC_RELAXED, __HIP_MEMORY_SCOPE_AGENT); }
; #define XB_SPIN(cond, bar) do { unsigned _sp = 0; while (cond) { __builtin_amdgcn_s_sleep(1); \
;     if ((++_sp & 255u) == 0u) { if (xb_ld(&(bar)[XB_TMO])) break; if (_sp > XB_SPIN_CAP) { atomicAdd(&(bar)[XB_TMO], 1u); break; } } } } while (0)
; __device__ __forceinline__ void xcd_barrier(const XcdBarrier& b) {
;     ...
;     if (threadIdx.x == 0) {
;         unsigned* bar = b.bar;
;         __builtin_amdgcn_s_waitcnt(0);
;         unsigned nloc = b.st[0], nx = b.st[1];
;         if (nloc == 0u) { xcd_barrier_complete(bar, b.x, nloc, nx); b.st[0] = nloc; b.st[1] = nx; }
;         const unsigned old = xb_add(&bar[XB_XSUB(b.x)], 1u);
;         const unsigned gen = old / nloc;
;         if (old + 1u == (gen + 1u) * nloc) {
;             __builtin_amdgcn_fence(__ATOMIC_RELEASE, "agent");
;             asm volatile("s_waitcnt vmcnt(0)" ::: "memory");
;             const unsigned og = xb_add(&bar[XB_TOP], 1u);
;             const unsigned tg = og / nx;
;             if (og + 1u == (tg + 1u) * nx) xb_add(&bar[XB_TOPGEN], 1u);
;             else XB_SPIN(xb_ld(&bar[XB_TOPGEN]) == tg, bar);
;             __builtin_amdgcn_fence(__ATOMIC_ACQUIRE, "agent");
;             xb_add(&bar[XB_XGEN(b.x)], 1u);
;             asm volatile("s_waitcnt vmcnt(0)" ::: "memory");
;         } else {
;             XB_SPIN(xb_ld(&bar[XB_XGEN(b.x)]) == gen, bar);
;             __builtin_amdgcn_fence(__ATOMIC_ACQUIRE, "agent");
;             asm volatile("s_waitcnt vmcnt(0)" ::: "memory");
;         }
.LBB0_785:
	s_or_b64 exec, exec, s[8:9]
	v_cvt_f32_u32_e32 v4, v2
	s_waitcnt vmcnt(0)
	v_readfirstlane_b32 s6, v3
	v_sub_u32_e32 v3, 0, v2
	v_rcp_iflag_f32_e32 v4, v4
	v_add_u32_e32 v5, s6, v0
	v_mul_f32_e32 v4, 0x4f7ffffe, v4
	v_cvt_u32_f32_e32 v4, v4
	v_mul_lo_u32 v0, v3, v4
	v_mul_hi_u32 v0, v4, v0
	v_add_u32_e32 v0, v4, v0
	v_mul_hi_u32 v0, v5, v0
	v_mul_lo_u32 v3, v0, v2
	v_sub_u32_e32 v3, v5, v3
	v_add_u32_e32 v4, 1, v0
	v_cmp_ge_u32_e32 vcc, v3, v2
	s_nop 1
	v_cndmask_b32_e32 v0, v0, v4, vcc
	v_sub_u32_e32 v4, v3, v2
	v_cndmask_b32_e32 v3, v3, v4, vcc
	v_add_u32_e32 v4, 1, v0
	v_cmp_ge_u32_e32 vcc, v3, v2
	v_add_u32_e32 v3, 1, v5
	s_nop 0
	v_cndmask_b32_e32 v0, v0, v4, vcc
	v_mul_lo_u32 v4, v2, v0
	v_add_u32_e32 v2, v4, v2
	v_cmp_ne_u32_e32 vcc, v3, v2
	s_and_saveexec_b64 s[6:7], vcc
	s_xor_b64 s[6:7], exec, s[6:7]
	s_cbranch_execz .LBB0_799
	s_waitcnt lgkmcnt(0)
	v_mad_u32_u24 v6, v0, v1, v1
	s_add_u32 s12, s22, 0x1e6c4400
	s_addc_u32 s13, s23, 0
	v_mov_b32_e32 v1, 0
	global_load_dword v1, v1, s[12:13] sc1
	s_waitcnt vmcnt(0)
	v_cmp_lt_u32_e32 vcc, v1, v6
	s_and_saveexec_b64 s[8:9], vcc
	s_cbranch_execz .LBB0_798
	s_add_u32 s10, s22, 0x1e6c1200
	s_addc_u32 s11, s23, 0
	s_mov_b32 s28, 1
	s_mov_b64 s[14:15], 0
	v_mov_b32_e32 v1, 0
	s_branch .LBB0_789

;   DI unsigned* bar() const { return (unsigned*)(ws + OFF_BAR); }
; __device__ __forceinline__ unsigned xb_ld(unsigned* p)              { return __hip_atomic_load(p, __ATOMIC_RELAXED, __HIP_MEMORY_SCOPE_AGENT); }
; __device__ __forceinline__ unsigned xb_add(unsigned* p, unsigned v) { return __hip_atomic_fetch_add(p, v, __ATOMIC_RELAXED, __HIP_MEMORY_SCOPE_AGENT); }
; #define XB_SPIN(cond, bar) do { unsigned _sp = 0; while (cond) { __builtin_amdgcn_s_sleep(1); \
;     if ((++_sp & 255u) == 0u) { if (xb_ld(&(bar)[XB_TMO])) break; if (_sp > XB_SPIN_CAP) { atomicAdd(&(bar)[XB_TMO], 1u); break; } } } } while (0)
; __device__ __forceinline__ void xcd_barrier(const XcdBarrier& b) {
;     ...
;             const unsigned og = xb_add(&bar[XB_TOP], 1u);
;             const unsigned tg = og / nx;
;             if (og + 1u == (tg + 1u) * nx) xb_add(&bar[XB_TOPGEN], 1u);
;             else XB_SPIN(xb_ld(&bar[XB_TOPGEN]) == tg, bar);
;             __builtin_amdgcn_fence(__ATOMIC_ACQUIRE, "agent");
;             xb_add(&bar[XB_XGEN(b.x)], 1u);
.LBB0_802:
	s_or_b64 exec, exec, s[8:9]
	v_cvt_f32_u32_e32 v3, v1
	s_waitcnt vmcnt(0)
	v_readfirstlane_b32 s6, v2
	s_add_u32 s8, s22, 0x1e6c4500
	s_addc_u32 s9, s23, 0
	s_add_u32 s98, s22, 0x1e6c4400
	s_addc_u32 s99, s23, 0
	v_rcp_iflag_f32_e32 v3, v3
	v_add_u32_e32 v0, s6, v0
	v_add_u32_e32 v4, 1, v0
	s_mov_b64 s[10:11], 0
	v_mul_f32_e32 v2, 0x4f7ffffe, v3
	v_cvt_u32_f32_e32 v2, v2
	v_sub_u32_e32 v3, 0, v1
	v_mul_lo_u32 v3, v3, v2
	v_mul_hi_u32 v3, v2, v3
	v_add_u32_e32 v2, v2, v3
	v_mul_hi_u32 v2, v0, v2
	v_mul_lo_u32 v3, v2, v1
	v_sub_u32_e32 v0, v0, v3
	v_add_u32_e32 v5, 1, v2
	v_cmp_ge_u32_e32 vcc, v0, v1
	v_sub_u32_e32 v3, v0, v1
	s_nop 0
	v_cndmask_b32_e32 v2, v2, v5, vcc
	v_cndmask_b32_e32 v0, v0, v3, vcc
	v_add_u32_e32 v3, 1, v2
	v_cmp_ge_u32_e32 vcc, v0, v1
	s_nop 1
	v_cndmask_b32_e32 v2, v2, v3, vcc
	v_mul_lo_u32 v0, v1, v2
	v_add_u32_e32 v0, v0, v1
	v_cmp_ne_u32_e32 vcc, v4, v0
	v_mov_b32_e32 v6, v0
	v_mov_b64_e32 v[0:1], s[8:9]
	s_and_saveexec_b64 s[6:7], vcc
	s_cbranch_execz .LBB0_814
	v_mov_b32_e32 v0, 0
	global_load_dword v1, v0, s[98:99] sc1
	s_mov_b64 s[14:15], 0
	s_waitcnt vmcnt(0)
	v_cmp_lt_u32_e32 vcc, v1, v6
	s_and_saveexec_b64 s[12:13], vcc
	s_cbranch_execz .LBB0_813
	s_add_u32 s10, s22, 0x1e6c1200
	s_addc_u32 s11, s23, 0
	s_mov_b32 s28, 1
	s_branch .LBB0_806

;   DI unsigned* bar() const { return (unsigned*)(ws + OFF_BAR); }
; __device__ __forceinline__ unsigned xb_add(unsigned* p, unsigned v) { return __hip_atomic_fetch_add(p, v, __ATOMIC_RELAXED, __HIP_MEMORY_SCOPE_AGENT); }
; __device__ __forceinline__ void xcd_barrier(const XcdBarrier& b) {
;     ...
;             __builtin_amdgcn_fence(__ATOMIC_ACQUIRE, "agent");
;             xb_add(&bar[XB_XGEN(b.x)], 1u);
;             asm volatile("s_waitcnt vmcnt(0)" ::: "memory");
.LBB0_816:
	s_or_b64 exec, exec, s[6:7]
	s_mov_b64 s[6:7], exec
	v_mbcnt_lo_u32_b32 v0, s6, 0
	v_mbcnt_hi_u32_b32 v0, s7, v0
	v_cmp_eq_u32_e32 vcc, 0, v0
	s_waitcnt vmcnt(0)
	buffer_inv sc1
	s_and_saveexec_b64 s[8:9], vcc
	s_cbranch_execz .LBB0_818
	s_bcnt1_i32_b64 s6, s[6:7]
	v_mov_b32_e32 v0, 0x2000
	v_mov_b32_e32 v1, s6
.LBB0_818:
	s_or_b64 exec, exec, s[8:9]
	s_waitcnt vmcnt(0)

;   DI unsigned* bar() const { return (unsigned*)(ws + OFF_BAR); }
; __device__ __forceinline__ unsigned xb_ld(unsigned* p)              { return __hip_atomic_load(p, __ATOMIC_RELAXED, __HIP_MEMORY_SCOPE_AGENT); }
; __device__ __forceinline__ unsigned xb_add(unsigned* p, unsigned v) { return __hip_atomic_fetch_add(p, v, __ATOMIC_RELAXED, __HIP_MEMORY_SCOPE_AGENT); }
; #define XB_SPIN(cond, bar) do { unsigned _sp = 0; while (cond) { __builtin_amdgcn_s_sleep(1); \
;     if ((++_sp & 255u) == 0u) { if (xb_ld(&(bar)[XB_TMO])) break; if (_sp > XB_SPIN_CAP) { atomicAdd(&(bar)[XB_TMO], 1u); break; } } } } while (0)
; __device__ __forceinline__ void xcd_barrier(const XcdBarrier& b) {
;     ...
;     if (threadIdx.x == 0) {
;         unsigned* bar = b.bar;
;         __builtin_amdgcn_s_waitcnt(0);
;         unsigned nloc = b.st[0], nx = b.st[1];
;         if (nloc == 0u) { xcd_barrier_complete(bar, b.x, nloc, nx); b.st[0] = nloc; b.st[1] = nx; }
;         const unsigned old = xb_add(&bar[XB_XSUB(b.x)], 1u);
;         const unsigned gen = old / nloc;
;         if (old + 1u == (gen + 1u) * nloc) {
;             __builtin_amdgcn_fence(__ATOMIC_RELEASE, "agent");
;             asm volatile("s_waitcnt vmcnt(0)" ::: "memory");
;             const unsigned og = xb_add(&bar[XB_TOP], 1u);
;             const unsigned tg = og / nx;
;             if (og + 1u == (tg + 1u) * nx) xb_add(&bar[XB_TOPGEN], 1u);
;             else XB_SPIN(xb_ld(&bar[XB_TOPGEN]) == tg, bar);
;             __builtin_amdgcn_fence(__ATOMIC_ACQUIRE, "agent");
;             xb_add(&bar[XB_XGEN(b.x)], 1u);
;             asm volatile("s_waitcnt vmcnt(0)" ::: "memory");
;         } else {
;             XB_SPIN(xb_ld(&bar[XB_XGEN(b.x)]) == gen, bar);
;             __builtin_amdgcn_fence(__ATOMIC_ACQUIRE, "agent");
;             asm volatile("s_waitcnt vmcnt(0)" ::: "memory");
;         }
.LBB0_840:
	s_or_b64 exec, exec, s[8:9]
	v_cvt_f32_u32_e32 v4, v2
	s_waitcnt vmcnt(0)
	v_readfirstlane_b32 s6, v3
	v_sub_u32_e32 v3, 0, v2
	v_rcp_iflag_f32_e32 v4, v4
	v_add_u32_e32 v5, s6, v0
	v_mul_f32_e32 v4, 0x4f7ffffe, v4
	v_cvt_u32_f32_e32 v4, v4
	v_mul_lo_u32 v0, v3, v4
	v_mul_hi_u32 v0, v4, v0
	v_add_u32_e32 v0, v4, v0
	v_mul_hi_u32 v0, v5, v0
	v_mul_lo_u32 v3, v0, v2
	v_sub_u32_e32 v3, v5, v3
	v_add_u32_e32 v4, 1, v0
	v_cmp_ge_u32_e32 vcc, v3, v2
	s_nop 1
	v_cndmask_b32_e32 v0, v0, v4, vcc
	v_sub_u32_e32 v4, v3, v2
	v_cndmask_b32_e32 v3, v3, v4, vcc
	v_add_u32_e32 v4, 1, v0
	v_cmp_ge_u32_e32 vcc, v3, v2
	v_add_u32_e32 v3, 1, v5
	s_nop 0
	v_cndmask_b32_e32 v0, v0, v4, vcc
	v_mul_lo_u32 v4, v2, v0
	v_add_u32_e32 v2, v4, v2
	v_cmp_ne_u32_e32 vcc, v3, v2
	s_and_saveexec_b64 s[6:7], vcc
	s_xor_b64 s[6:7], exec, s[6:7]
	s_cbranch_execz .LBB0_854
	s_waitcnt lgkmcnt(0)
	v_mad_u32_u24 v6, v0, v1, v1
	s_add_u32 s12, s22, 0x1e6c4400
	s_addc_u32 s13, s23, 0
	v_mov_b32_e32 v1, 0
	global_load_dword v1, v1, s[12:13] sc1
	s_waitcnt vmcnt(0)
	v_cmp_lt_u32_e32 vcc, v1, v6
	s_and_saveexec_b64 s[8:9], vcc
	s_cbranch_execz .LBB0_853
	s_add_u32 s10, s22, 0x1e6c1200
	s_addc_u32 s11, s23, 0
	s_mov_b32 s27, 1
	s_mov_b64 s[14:15], 0
	v_mov_b32_e32 v1, 0
	s_branch .LBB0_844

;   DI unsigned* bar() const { return (unsigned*)(ws + OFF_BAR); }
; __device__ __forceinline__ unsigned xb_ld(unsigned* p)              { return __hip_atomic_load(p, __ATOMIC_RELAXED, __HIP_MEMORY_SCOPE_AGENT); }
; __device__ __forceinline__ unsigned xb_add(unsigned* p, unsigned v) { return __hip_atomic_fetch_add(p, v, __ATOMIC_RELAXED, __HIP_MEMORY_SCOPE_AGENT); }
; #define XB_SPIN(cond, bar) do { unsigned _sp = 0; while (cond) { __builtin_amdgcn_s_sleep(1); \
;     if ((++_sp & 255u) == 0u) { if (xb_ld(&(bar)[XB_TMO])) break; if (_sp > XB_SPIN_CAP) { atomicAdd(&(bar)[XB_TMO], 1u); break; } } } } while (0)
; __device__ __forceinline__ void xcd_barrier(const XcdBarrier& b) {
;     ...
;             else XB_SPIN(xb_ld(&bar[XB_TOPGEN]) == tg, bar);
;             __builtin_amdgcn_fence(__ATOMIC_ACQUIRE, "agent");
;             xb_add(&bar[XB_XGEN(b.x)], 1u);
;             asm volatile("s_waitcnt vmcnt(0)" ::: "memory");
;         } else {
;             XB_SPIN(xb_ld(&bar[XB_XGEN(b.x)]) == gen, bar);
.LBB0_848:
	global_load_dword v2, v1, s[12:13] sc1
	s_add_i32 s27, s27, 1
	s_mov_b64 s[24:25], -1
	s_waitcnt vmcnt(0)
	v_cmp_ge_u32_e32 vcc, v2, v6
	s_orn2_b64 s[18:19], vcc, exec
	s_branch .LBB0_843

;   DI unsigned* bar() const { return (unsigned*)(ws + OFF_BAR); }
; __device__ __forceinline__ unsigned xb_ld(unsigned* p)              { return __hip_atomic_load(p, __ATOMIC_RELAXED, __HIP_MEMORY_SCOPE_AGENT); }
; __device__ __forceinline__ unsigned xb_add(unsigned* p, unsigned v) { return __hip_atomic_fetch_add(p, v, __ATOMIC_RELAXED, __HIP_MEMORY_SCOPE_AGENT); }
; #define XB_SPIN(cond, bar) do { unsigned _sp = 0; while (cond) { __builtin_amdgcn_s_sleep(1); \
;     if ((++_sp & 255u) == 0u) { if (xb_ld(&(bar)[XB_TMO])) break; if (_sp > XB_SPIN_CAP) { atomicAdd(&(bar)[XB_TMO], 1u); break; } } } } while (0)
; __device__ __forceinline__ void xcd_barrier(const XcdBarrier& b) {
;     ...
;             const unsigned og = xb_add(&bar[XB_TOP], 1u);
;             const unsigned tg = og / nx;
;             if (og + 1u == (tg + 1u) * nx) xb_add(&bar[XB_TOPGEN], 1u);
;             else XB_SPIN(xb_ld(&bar[XB_TOPGEN]) == tg, bar);
;             __builtin_amdgcn_fence(__ATOMIC_ACQUIRE, "agent");
;             xb_add(&bar[XB_XGEN(b.x)], 1u);
.LBB0_857:
	s_or_b64 exec, exec, s[8:9]
	v_cvt_f32_u32_e32 v3, v1
	s_waitcnt vmcnt(0)
	v_readfirstlane_b32 s6, v2
	s_add_u32 s8, s22, 0x1e6c4500
	s_addc_u32 s9, s23, 0
	s_add_u32 s98, s22, 0x1e6c4400
	s_addc_u32 s99, s23, 0
	v_rcp_iflag_f32_e32 v3, v3
	v_add_u32_e32 v0, s6, v0
	v_add_u32_e32 v4, 1, v0
	s_mov_b64 s[10:11], 0
	v_mul_f32_e32 v2, 0x4f7ffffe, v3
	v_cvt_u32_f32_e32 v2, v2
	v_sub_u32_e32 v3, 0, v1
	v_mul_lo_u32 v3, v3, v2
	v_mul_hi_u32 v3, v2, v3
	v_add_u32_e32 v2, v2, v3
	v_mul_hi_u32 v2, v0, v2
	v_mul_lo_u32 v3, v2, v1
	v_sub_u32_e32 v0, v0, v3
	v_add_u32_e32 v5, 1, v2
	v_cmp_ge_u32_e32 vcc, v0, v1
	v_sub_u32_e32 v3, v0, v1
	s_nop 0
	v_cndmask_b32_e32 v2, v2, v5, vcc
	v_cndmask_b32_e32 v0, v0, v3, vcc
	v_add_u32_e32 v3, 1, v2
	v_cmp_ge_u32_e32 vcc, v0, v1
	s_nop 1
	v_cndmask_b32_e32 v2, v2, v3, vcc
	v_mul_lo_u32 v0, v1, v2
	v_add_u32_e32 v0, v0, v1
	v_cmp_ne_u32_e32 vcc, v4, v0
	v_mov_b32_e32 v6, v0
	v_mov_b64_e32 v[0:1], s[8:9]
	s_and_saveexec_b64 s[6:7], vcc
	s_cbranch_execz .LBB0_869
	v_mov_b32_e32 v0, 0
	global_load_dword v1, v0, s[98:99] sc1
	s_mov_b64 s[14:15], 0
	s_waitcnt vmcnt(0)
	v_cmp_lt_u32_e32 vcc, v1, v6
	s_and_saveexec_b64 s[12:13], vcc
	s_cbranch_execz .LBB0_868
	s_add_u32 s10, s22, 0x1e6c1200
	s_addc_u32 s11, s23, 0
	s_mov_b32 s27, 1
	s_branch .LBB0_861

;   DI unsigned* bar() const { return (unsigned*)(ws + OFF_BAR); }
; __device__ __forceinline__ unsigned xb_ld(unsigned* p)              { return __hip_atomic_load(p, __ATOMIC_RELAXED, __HIP_MEMORY_SCOPE_AGENT); }
; __device__ __forceinline__ unsigned xb_add(unsigned* p, unsigned v) { return __hip_atomic_fetch_add(p, v, __ATOMIC_RELAXED, __HIP_MEMORY_SCOPE_AGENT); }
; #define XB_SPIN(cond, bar) do { unsigned _sp = 0; while (cond) { __builtin_amdgcn_s_sleep(1); \
;     if ((++_sp & 255u) == 0u) { if (xb_ld(&(bar)[XB_TMO])) break; if (_sp > XB_SPIN_CAP) { atomicAdd(&(bar)[XB_TMO], 1u); break; } } } } while (0)
; __device__ __forceinline__ void xcd_barrier(const XcdBarrier& b) {
;     ...
;             const unsigned og = xb_add(&bar[XB_TOP], 1u);
;             const unsigned tg = og / nx;
;             if (og + 1u == (tg + 1u) * nx) xb_add(&bar[XB_TOPGEN], 1u);
;             else XB_SPIN(xb_ld(&bar[XB_TOPGEN]) == tg, bar);
;             __builtin_amdgcn_fence(__ATOMIC_ACQUIRE, "agent");
;             xb_add(&bar[XB_XGEN(b.x)], 1u);
.LBB0_865:
	global_load_dword v1, v0, s[98:99] sc1
	s_add_i32 s27, s27, 1
	s_mov_b64 s[18:19], -1
	s_waitcnt vmcnt(0)
	v_cmp_ge_u32_e32 vcc, v1, v6
	s_orn2_b64 s[28:29], vcc, exec
	s_branch .LBB0_860

;   DI unsigned* bar() const { return (unsigned*)(ws + OFF_BAR); }
; __device__ __forceinline__ unsigned xb_add(unsigned* p, unsigned v) { return __hip_atomic_fetch_add(p, v, __ATOMIC_RELAXED, __HIP_MEMORY_SCOPE_AGENT); }
; __device__ __forceinline__ void xcd_barrier(const XcdBarrier& b) {
;     ...
;             __builtin_amdgcn_fence(__ATOMIC_ACQUIRE, "agent");
;             xb_add(&bar[XB_XGEN(b.x)], 1u);
;             asm volatile("s_waitcnt vmcnt(0)" ::: "memory");
.LBB0_871:
	s_or_b64 exec, exec, s[6:7]
	s_mov_b64 s[6:7], exec
	v_mbcnt_lo_u32_b32 v0, s6, 0
	v_mbcnt_hi_u32_b32 v0, s7, v0
	v_cmp_eq_u32_e32 vcc, 0, v0
	s_waitcnt vmcnt(0)
	buffer_inv sc1
	s_and_saveexec_b64 s[8:9], vcc
	s_cbranch_execz .LBB0_873
	s_bcnt1_i32_b64 s6, s[6:7]
	v_mov_b32_e32 v0, 0x2000
	v_mov_b32_e32 v1, s6
.LBB0_873:
	s_or_b64 exec, exec, s[8:9]
	s_waitcnt vmcnt(0)

;   DI unsigned* bar() const { return (unsigned*)(ws + OFF_BAR); }
; __device__ __forceinline__ unsigned xb_add(unsigned* p, unsigned v) { return __hip_atomic_fetch_add(p, v, __ATOMIC_RELAXED, __HIP_MEMORY_SCOPE_AGENT); }
; __device__ __forceinline__ void xcd_barrier(const XcdBarrier& b) {
;     ...
;             __builtin_amdgcn_fence(__ATOMIC_ACQUIRE, "agent");
;             xb_add(&bar[XB_XGEN(b.x)], 1u);
;             asm volatile("s_waitcnt vmcnt(0)" ::: "memory");
.LBB0_965:
	s_or_b64 exec, exec, s[6:7]
	s_mov_b64 s[6:7], exec
	v_mbcnt_lo_u32_b32 v0, s6, 0
	v_mbcnt_hi_u32_b32 v0, s7, v0
	v_cmp_eq_u32_e32 vcc, 0, v0
	s_waitcnt vmcnt(0)
	buffer_inv sc1
	s_and_saveexec_b64 s[8:9], vcc
	s_cbranch_execz .LBB0_967
	s_bcnt1_i32_b64 s6, s[6:7]
	v_mov_b32_e32 v0, 0x2000
	v_mov_b32_e32 v1, s6
.LBB0_967:
	s_or_b64 exec, exec, s[8:9]
	s_waitcnt vmcnt(0)

;   DI unsigned* bar() const { return (unsigned*)(ws + OFF_BAR); }
; __device__ __forceinline__ unsigned xb_add(unsigned* p, unsigned v) { return __hip_atomic_fetch_add(p, v, __ATOMIC_RELAXED, __HIP_MEMORY_SCOPE_AGENT); }
; __device__ __forceinline__ void xcd_barrier(const XcdBarrier& b) {
;     ...
;             __builtin_amdgcn_fence(__ATOMIC_ACQUIRE, "agent");
;             xb_add(&bar[XB_XGEN(b.x)], 1u);
;             asm volatile("s_waitcnt vmcnt(0)" ::: "memory");
.LBB0_1358:
	s_or_b64 exec, exec, s[6:7]
	s_mov_b64 s[6:7], exec
	v_mbcnt_lo_u32_b32 v0, s6, 0
	v_mbcnt_hi_u32_b32 v0, s7, v0
	v_cmp_eq_u32_e32 vcc, 0, v0
	s_waitcnt vmcnt(0)
	buffer_inv sc1
	s_and_saveexec_b64 s[8:9], vcc
	s_cbranch_execz .LBB0_1360
	s_bcnt1_i32_b64 s6, s[6:7]
	v_mov_b32_e32 v0, 0x2000
	v_mov_b32_e32 v1, s6
.LBB0_1360:
	s_or_b64 exec, exec, s[8:9]
	s_waitcnt vmcnt(0)

;   DI unsigned* bar() const { return (unsigned*)(ws + OFF_BAR); }
; __device__ __forceinline__ unsigned xb_ld(unsigned* p)              { return __hip_atomic_load(p, __ATOMIC_RELAXED, __HIP_MEMORY_SCOPE_AGENT); }
; __device__ __forceinline__ unsigned xb_add(unsigned* p, unsigned v) { return __hip_atomic_fetch_add(p, v, __ATOMIC_RELAXED, __HIP_MEMORY_SCOPE_AGENT); }
; #define XB_SPIN(cond, bar) do { unsigned _sp = 0; while (cond) { __builtin_amdgcn_s_sleep(1); \
;     if ((++_sp & 255u) == 0u) { if (xb_ld(&(bar)[XB_TMO])) break; if (_sp > XB_SPIN_CAP) { atomicAdd(&(bar)[XB_TMO], 1u); break; } } } } while (0)
; __device__ __forceinline__ void xcd_barrier(const XcdBarrier& b) {
;     ...
;             const unsigned og = xb_add(&bar[XB_TOP], 1u);
;             const unsigned tg = og / nx;
;             if (og + 1u == (tg + 1u) * nx) xb_add(&bar[XB_TOPGEN], 1u);
;             else XB_SPIN(xb_ld(&bar[XB_TOPGEN]) == tg, bar);
;             __builtin_amdgcn_fence(__ATOMIC_ACQUIRE, "agent");
;             xb_add(&bar[XB_XGEN(b.x)], 1u);
.LBB0_1621:
	global_load_dword v1, v0, s[98:99] sc1
	s_add_i32 s27, s27, 1
	s_mov_b64 s[18:19], -1
	s_waitcnt vmcnt(0)
	v_cmp_ge_u32_e32 vcc, v1, v6
	s_orn2_b64 s[30:31], vcc, exec
	s_branch .LBB0_1616

;   DI unsigned* bar() const { return (unsigned*)(ws + OFF_BAR); }
; __device__ __forceinline__ unsigned xb_add(unsigned* p, unsigned v) { return __hip_atomic_fetch_add(p, v, __ATOMIC_RELAXED, __HIP_MEMORY_SCOPE_AGENT); }
; __device__ __forceinline__ void xcd_barrier(const XcdBarrier& b) {
;     ...
;             __builtin_amdgcn_fence(__ATOMIC_ACQUIRE, "agent");
;             xb_add(&bar[XB_XGEN(b.x)], 1u);
;             asm volatile("s_waitcnt vmcnt(0)" ::: "memory");
.LBB0_1627:
	s_or_b64 exec, exec, s[6:7]
	s_mov_b64 s[6:7], exec
	v_mbcnt_lo_u32_b32 v0, s6, 0
	v_mbcnt_hi_u32_b32 v0, s7, v0
	v_cmp_eq_u32_e32 vcc, 0, v0
	s_waitcnt vmcnt(0)
	buffer_inv sc1
	s_and_saveexec_b64 s[8:9], vcc
	s_cbranch_execz .LBB0_1629
	s_bcnt1_i32_b64 s6, s[6:7]
	v_mov_b32_e32 v0, 0x2000
	v_mov_b32_e32 v1, s6
.LBB0_1629:
	s_or_b64 exec, exec, s[8:9]
	s_waitcnt vmcnt(0)

;   DI unsigned* bar() const { return (unsigned*)(ws + OFF_BAR); }
; __device__ __forceinline__ unsigned xb_ld(unsigned* p)              { return __hip_atomic_load(p, __ATOMIC_RELAXED, __HIP_MEMORY_SCOPE_AGENT); }
; __device__ __forceinline__ unsigned xb_add(unsigned* p, unsigned v) { return __hip_atomic_fetch_add(p, v, __ATOMIC_RELAXED, __HIP_MEMORY_SCOPE_AGENT); }
; #define XB_SPIN(cond, bar) do { unsigned _sp = 0; while (cond) { __builtin_amdgcn_s_sleep(1); \
;     if ((++_sp & 255u) == 0u) { if (xb_ld(&(bar)[XB_TMO])) break; if (_sp > XB_SPIN_CAP) { atomicAdd(&(bar)[XB_TMO], 1u); break; } } } } while (0)
; __device__ __forceinline__ void xcd_barrier(const XcdBarrier& b) {
;     ...
;     if (threadIdx.x == 0) {
;         unsigned* bar = b.bar;
;         __builtin_amdgcn_s_waitcnt(0);
;         unsigned nloc = b.st[0], nx = b.st[1];
;         if (nloc == 0u) { xcd_barrier_complete(bar, b.x, nloc, nx); b.st[0] = nloc; b.st[1] = nx; }
;         const unsigned old = xb_add(&bar[XB_XSUB(b.x)], 1u);
;         const unsigned gen = old / nloc;
;         if (old + 1u == (gen + 1u) * nloc) {
;             __builtin_amdgcn_fence(__ATOMIC_RELEASE, "agent");
;             asm volatile("s_waitcnt vmcnt(0)" ::: "memory");
;             const unsigned og = xb_add(&bar[XB_TOP], 1u);
;             const unsigned tg = og / nx;
;             if (og + 1u == (tg + 1u) * nx) xb_add(&bar[XB_TOPGEN], 1u);
;             else XB_SPIN(xb_ld(&bar[XB_TOPGEN]) == tg, bar);
;             __builtin_amdgcn_fence(__ATOMIC_ACQUIRE, "agent");
;             xb_add(&bar[XB_XGEN(b.x)], 1u);
;             asm volatile("s_waitcnt vmcnt(0)" ::: "memory");
;         } else {
;             XB_SPIN(xb_ld(&bar[XB_XGEN(b.x)]) == gen, bar);
;             __builtin_amdgcn_fence(__ATOMIC_ACQUIRE, "agent");
;             asm volatile("s_waitcnt vmcnt(0)" ::: "memory");
;         }
.LBB0_1673:
	s_or_b64 exec, exec, s[6:7]
	v_cvt_f32_u32_e32 v4, v2
	s_waitcnt vmcnt(0)
	v_readfirstlane_b32 s4, v3
	v_sub_u32_e32 v3, 0, v2
	v_rcp_iflag_f32_e32 v4, v4
	v_add_u32_e32 v5, s4, v0
	v_mul_f32_e32 v4, 0x4f7ffffe, v4
	v_cvt_u32_f32_e32 v4, v4
	v_mul_lo_u32 v0, v3, v4
	v_mul_hi_u32 v0, v4, v0
	v_add_u32_e32 v0, v4, v0
	v_mul_hi_u32 v0, v5, v0
	v_mul_lo_u32 v3, v0, v2
	v_sub_u32_e32 v3, v5, v3
	v_add_u32_e32 v4, 1, v0
	v_cmp_ge_u32_e32 vcc, v3, v2
	s_nop 1
	v_cndmask_b32_e32 v0, v0, v4, vcc
	v_sub_u32_e32 v4, v3, v2
	v_cndmask_b32_e32 v3, v3, v4, vcc
	v_add_u32_e32 v4, 1, v0
	v_cmp_ge_u32_e32 vcc, v3, v2
	v_add_u32_e32 v3, 1, v5
	s_nop 0
	v_cndmask_b32_e32 v0, v0, v4, vcc
	v_mul_lo_u32 v4, v2, v0
	v_add_u32_e32 v2, v4, v2
	v_cmp_ne_u32_e32 vcc, v3, v2
	s_and_saveexec_b64 s[4:5], vcc
	s_xor_b64 s[4:5], exec, s[4:5]
	s_cbranch_execz .LBB0_1687
	s_waitcnt lgkmcnt(0)
	v_mad_u32_u24 v6, v0, v1, v1
	s_add_u32 s10, s22, 0x1e6c4400
	s_addc_u32 s11, s23, 0
	v_mov_b32_e32 v1, 0
	global_load_dword v1, v1, s[10:11] sc1
	s_waitcnt vmcnt(0)
	v_cmp_lt_u32_e32 vcc, v1, v6
	s_and_saveexec_b64 s[6:7], vcc
	s_cbranch_execz .LBB0_1686
	s_add_u32 s8, s22, 0x1e6c1200
	s_addc_u32 s9, s23, 0
	s_mov_b32 s27, 1
	s_mov_b64 s[12:13], 0
	v_mov_b32_e32 v1, 0
	s_branch .LBB0_1677

;   DI unsigned* bar() const { return (unsigned*)(ws + OFF_BAR); }
; __device__ __forceinline__ unsigned xb_ld(unsigned* p)              { return __hip_atomic_load(p, __ATOMIC_RELAXED, __HIP_MEMORY_SCOPE_AGENT); }
; __device__ __forceinline__ unsigned xb_add(unsigned* p, unsigned v) { return __hip_atomic_fetch_add(p, v, __ATOMIC_RELAXED, __HIP_MEMORY_SCOPE_AGENT); }
; #define XB_SPIN(cond, bar) do { unsigned _sp = 0; while (cond) { __builtin_amdgcn_s_sleep(1); \
;     if ((++_sp & 255u) == 0u) { if (xb_ld(&(bar)[XB_TMO])) break; if (_sp > XB_SPIN_CAP) { atomicAdd(&(bar)[XB_TMO], 1u); break; } } } } while (0)
; __device__ __forceinline__ void xcd_barrier(const XcdBarrier& b) {
;     ...
;             else XB_SPIN(xb_ld(&bar[XB_TOPGEN]) == tg, bar);
;             __builtin_amdgcn_fence(__ATOMIC_ACQUIRE, "agent");
;             xb_add(&bar[XB_XGEN(b.x)], 1u);
;             asm volatile("s_waitcnt vmcnt(0)" ::: "memory");
;         } else {
;             XB_SPIN(xb_ld(&bar[XB_XGEN(b.x)]) == gen, bar);
.LBB0_1681:
	global_load_dword v2, v1, s[10:11] sc1
	s_add_i32 s27, s27, 1
	s_mov_b64 s[18:19], -1
	s_waitcnt vmcnt(0)
	v_cmp_ge_u32_e32 vcc, v2, v6
	s_orn2_b64 s[16:17], vcc, exec
	s_branch .LBB0_1676

;   DI unsigned* bar() const { return (unsigned*)(ws + OFF_BAR); }
; __device__ __forceinline__ unsigned xb_ld(unsigned* p)              { return __hip_atomic_load(p, __ATOMIC_RELAXED, __HIP_MEMORY_SCOPE_AGENT); }
; __device__ __forceinline__ unsigned xb_add(unsigned* p, unsigned v) { return __hip_atomic_fetch_add(p, v, __ATOMIC_RELAXED, __HIP_MEMORY_SCOPE_AGENT); }
; #define XB_SPIN(cond, bar) do { unsigned _sp = 0; while (cond) { __builtin_amdgcn_s_sleep(1); \
;     if ((++_sp & 255u) == 0u) { if (xb_ld(&(bar)[XB_TMO])) break; if (_sp > XB_SPIN_CAP) { atomicAdd(&(bar)[XB_TMO], 1u); break; } } } } while (0)
; __device__ __forceinline__ void xcd_barrier(const XcdBarrier& b) {
;     ...
;             const unsigned og = xb_add(&bar[XB_TOP], 1u);
;             const unsigned tg = og / nx;
;             if (og + 1u == (tg + 1u) * nx) xb_add(&bar[XB_TOPGEN], 1u);
;             else XB_SPIN(xb_ld(&bar[XB_TOPGEN]) == tg, bar);
;             __builtin_amdgcn_fence(__ATOMIC_ACQUIRE, "agent");
;             xb_add(&bar[XB_XGEN(b.x)], 1u);
.LBB0_1690:
	s_or_b64 exec, exec, s[6:7]
	v_cvt_f32_u32_e32 v3, v1
	s_waitcnt vmcnt(0)
	v_readfirstlane_b32 s4, v2
	s_add_u32 s6, s22, 0x1e6c4500
	s_addc_u32 s7, s23, 0
	s_add_u32 s98, s22, 0x1e6c4400
	s_addc_u32 s99, s23, 0
	v_rcp_iflag_f32_e32 v3, v3
	v_add_u32_e32 v0, s4, v0
	v_add_u32_e32 v4, 1, v0
	s_mov_b64 s[8:9], 0
	v_mul_f32_e32 v2, 0x4f7ffffe, v3
	v_cvt_u32_f32_e32 v2, v2
	v_sub_u32_e32 v3, 0, v1
	v_mul_lo_u32 v3, v3, v2
	v_mul_hi_u32 v3, v2, v3
	v_add_u32_e32 v2, v2, v3
	v_mul_hi_u32 v2, v0, v2
	v_mul_lo_u32 v3, v2, v1
	v_sub_u32_e32 v0, v0, v3
	v_add_u32_e32 v5, 1, v2
	v_cmp_ge_u32_e32 vcc, v0, v1
	v_sub_u32_e32 v3, v0, v1
	s_nop 0
	v_cndmask_b32_e32 v2, v2, v5, vcc
	v_cndmask_b32_e32 v0, v0, v3, vcc
	v_add_u32_e32 v3, 1, v2
	v_cmp_ge_u32_e32 vcc, v0, v1
	s_nop 1
	v_cndmask_b32_e32 v2, v2, v3, vcc
	v_mul_lo_u32 v0, v1, v2
	v_add_u32_e32 v0, v0, v1
	v_cmp_ne_u32_e32 vcc, v4, v0
	v_mov_b32_e32 v6, v0
	v_mov_b64_e32 v[0:1], s[6:7]
	s_and_saveexec_b64 s[4:5], vcc
	s_cbranch_execz .LBB0_1702
	v_mov_b32_e32 v0, 0
	global_load_dword v1, v0, s[98:99] sc1
	s_mov_b64 s[12:13], 0
	s_waitcnt vmcnt(0)
	v_cmp_lt_u32_e32 vcc, v1, v6
	s_and_saveexec_b64 s[10:11], vcc
	s_cbranch_execz .LBB0_1701
	s_add_u32 s8, s22, 0x1e6c1200
	s_addc_u32 s9, s23, 0
	s_mov_b32 s24, 1
	s_branch .LBB0_1694

;   DI unsigned* bar() const { return (unsigned*)(ws + OFF_BAR); }
; __device__ __forceinline__ unsigned xb_ld(unsigned* p)              { return __hip_atomic_load(p, __ATOMIC_RELAXED, __HIP_MEMORY_SCOPE_AGENT); }
; __device__ __forceinline__ unsigned xb_add(unsigned* p, unsigned v) { return __hip_atomic_fetch_add(p, v, __ATOMIC_RELAXED, __HIP_MEMORY_SCOPE_AGENT); }
; #define XB_SPIN(cond, bar) do { unsigned _sp = 0; while (cond) { __builtin_amdgcn_s_sleep(1); \
;     if ((++_sp & 255u) == 0u) { if (xb_ld(&(bar)[XB_TMO])) break; if (_sp > XB_SPIN_CAP) { atomicAdd(&(bar)[XB_TMO], 1u); break; } } } } while (0)
; __device__ __forceinline__ void xcd_barrier(const XcdBarrier& b) {
;     ...
;             const unsigned og = xb_add(&bar[XB_TOP], 1u);
;             const unsigned tg = og / nx;
;             if (og + 1u == (tg + 1u) * nx) xb_add(&bar[XB_TOPGEN], 1u);
;             else XB_SPIN(xb_ld(&bar[XB_TOPGEN]) == tg, bar);
;             __builtin_amdgcn_fence(__ATOMIC_ACQUIRE, "agent");
;             xb_add(&bar[XB_XGEN(b.x)], 1u);
.LBB0_1698:
	global_load_dword v1, v0, s[98:99] sc1
	s_add_i32 s24, s24, 1
	s_mov_b64 s[16:17], -1
	s_waitcnt vmcnt(0)
	v_cmp_ge_u32_e32 vcc, v1, v6
	s_orn2_b64 s[22:23], vcc, exec
	s_branch .LBB0_1693

;   DI unsigned* bar() const { return (unsigned*)(ws + OFF_BAR); }
; __device__ __forceinline__ unsigned xb_add(unsigned* p, unsigned v) { return __hip_atomic_fetch_add(p, v, __ATOMIC_RELAXED, __HIP_MEMORY_SCOPE_AGENT); }
; __device__ __forceinline__ void xcd_barrier(const XcdBarrier& b) {
;     ...
;             __builtin_amdgcn_fence(__ATOMIC_ACQUIRE, "agent");
;             xb_add(&bar[XB_XGEN(b.x)], 1u);
;             asm volatile("s_waitcnt vmcnt(0)" ::: "memory");
.LBB0_1704:
	s_or_b64 exec, exec, s[4:5]
	s_mov_b64 s[4:5], exec
	v_mbcnt_lo_u32_b32 v0, s4, 0
	v_mbcnt_hi_u32_b32 v0, s5, v0
	v_cmp_eq_u32_e32 vcc, 0, v0
	s_waitcnt vmcnt(0)
	buffer_inv sc1
	s_and_saveexec_b64 s[6:7], vcc
	s_cbranch_execz .LBB0_1706
	s_bcnt1_i32_b64 s4, s[4:5]
	v_mov_b32_e32 v0, 0x2000
	v_mov_b32_e32 v1, s4
.LBB0_1706:
	s_or_b64 exec, exec, s[6:7]
	s_waitcnt vmcnt(0)
